# scan: solve-matrix rows padded to 80 B (conflict-free b128 row reads by the DPP solve)
# baseline (speedup 1.0000x reference)
.LBB0_391:
	s_andn2_saveexec_b64 s[20:21], s[78:79]
	v_subrev_u32_e32 v19, 0x17900, v151
	v_lshrrev_b32_e32 v19, 2, v19
	v_add3_u32 v19, v151, v145, v19
	ds_write_b128 v19, v[14:17]

.Lsx0_c:
	s_or_b64 exec, exec, s[2:3]
	v_mov_b32_e32 v22, 0
	v_mov_b32_e32 v23, 0
	v_mov_b32_e32 v24, 0
	v_mov_b32_e32 v25, 0
	s_and_saveexec_b64 s[2:3], s[56:57]
	s_cbranch_execz .LBB0_403
	ds_read_b128 v[48:51], v174
	ds_read_b128 v[60:63], v192 offset:49152
	ds_read_b128 v[52:55], v174 offset:64
	ds_read_b128 v[64:67], v192 offset:49216
	ds_read_b128 v[56:59], v175
	ds_read_b128 v[68:71], v199
	ds_read_b128 v[72:75], v192 offset:58368
	ds_read_b128 v[76:79], v192 offset:58432
	v_subrev_u32_e32 v96, 0x17900, v151
	v_lshrrev_b32_e32 v96, 2, v96
	v_add_u32_e32 v96, v151, v96
	ds_read_b128 v[80:83], v96
	ds_read_b128 v[84:87], v96 offset:16
	ds_read_b128 v[88:91], v96 offset:32
	ds_read_b128 v[92:95], v96 offset:48
	s_waitcnt lgkmcnt(10)
	v_mfma_f32_16x16x32_bf16 v[30:33], v[48:51], v[60:63], 0
	s_waitcnt lgkmcnt(8)
	v_mfma_f32_16x16x32_bf16 v[30:33], v[52:55], v[64:67], v[30:33]
	s_waitcnt lgkmcnt(6)
	v_mfma_f32_16x16x32_bf16 v[30:33], v[56:59], v[68:71], v[30:33]
	s_waitcnt lgkmcnt(5)
	v_mfma_f32_16x16x32_bf16 v[22:25], v[48:51], v[72:75], 0
	s_waitcnt lgkmcnt(4)
	v_mfma_f32_16x16x32_bf16 v[22:25], v[52:55], v[76:79], v[22:25]
	s_cmp_eq_u32 s36, 0
	s_cbranch_scc1 .Lis0b
	s_cmp_gt_u32 s36, 62
	s_cbranch_scc1 .Lis0b
	s_add_i32 s24, s19, 0xffffffc0
	s_add_i32 s25, s21, 0x30
	s_and_b64 s[98:99], s[12:13], exec
	s_cselect_b32 s24, s25, s24
	v_lshl_add_u32 v194, s24, 6, v183
	v_lshlrev_b32_e32 v112, 1, v194
	global_load_dword v5, v112, s[44:45]
	global_load_dword v207, v112, s[44:45] offset:-1024
	global_load_dword v6, v112, s[42:43]
	global_load_dword v208, v112, s[42:43] offset:-1024
	global_load_dword v7, v112, s[0:1]
	global_load_dword v209, v112, s[0:1] offset:-1024
	global_load_dword v8, v112, s[34:35]
	global_load_dword v210, v112, s[34:35] offset:-1024
	global_load_dword v9, v112, s[76:77]
	global_load_dword v211, v112, s[76:77] offset:-1024
	v_add_u32_e32 v194, s24, v184
	v_lshlrev_b32_e32 v114, 2, v194
	global_load_dword v110, v114, s[40:41]
	global_load_dword v212, v114, s[40:41] offset:-32

.LBB0_420:
	s_andn2_saveexec_b64 s[68:69], s[74:75]
	v_subrev_u32_e32 v26, 0x17900, v151
	v_lshrrev_b32_e32 v26, 2, v26
	v_add3_u32 v26, v151, v145, v26
	ds_write_b128 v26, v[22:25]

.Lsx1_c:
	s_or_b64 exec, exec, s[74:75]
	v_mov_b32_e32 v22, 0
	v_mov_b32_e32 v23, 0
	v_mov_b32_e32 v24, 0
	v_mov_b32_e32 v25, 0
	s_and_saveexec_b64 s[74:75], s[56:57]
	s_cbranch_execz .LBB0_432
	ds_read_b128 v[48:51], v174
	ds_read_b128 v[60:63], v192 offset:51456
	ds_read_b128 v[52:55], v174 offset:64
	ds_read_b128 v[64:67], v192 offset:51520
	ds_read_b128 v[56:59], v175 offset:5120
	ds_read_b128 v[68:71], v199
	ds_read_b128 v[72:75], v192 offset:60672
	ds_read_b128 v[76:79], v192 offset:60736
	v_subrev_u32_e32 v96, 0x17900, v151
	v_lshrrev_b32_e32 v96, 2, v96
	v_add_u32_e32 v96, v151, v96
	ds_read_b128 v[80:83], v96
	ds_read_b128 v[84:87], v96 offset:16
	ds_read_b128 v[88:91], v96 offset:32
	ds_read_b128 v[92:95], v96 offset:48
	s_waitcnt lgkmcnt(10)
	v_mfma_f32_16x16x32_bf16 v[30:33], v[48:51], v[60:63], 0
	s_waitcnt lgkmcnt(8)
	v_mfma_f32_16x16x32_bf16 v[30:33], v[52:55], v[64:67], v[30:33]
	s_waitcnt lgkmcnt(6)
	v_mfma_f32_16x16x32_bf16 v[30:33], v[56:59], v[68:71], v[30:33]
	s_waitcnt lgkmcnt(5)
	v_mfma_f32_16x16x32_bf16 v[22:25], v[48:51], v[72:75], 0
	s_waitcnt lgkmcnt(4)
	v_mfma_f32_16x16x32_bf16 v[22:25], v[52:55], v[76:79], v[22:25]
	s_cmp_gt_u32 s36, 61
	s_cbranch_scc1 .Lis1bw
	s_add_i32 s24, s19, 0xffffffb0
	s_add_i32 s25, s21, 64
	s_and_b64 s[98:99], s[12:13], exec
	s_cselect_b32 s24, s25, s24
	v_lshl_add_u32 v194, s24, 6, v183
	v_lshlrev_b32_e32 v112, 1, v194
	global_load_dword v0, v112, s[44:45]
	global_load_dword v201, v112, s[44:45] offset:-1024
	global_load_dword v1, v112, s[42:43]
	global_load_dword v202, v112, s[42:43] offset:-1024
	global_load_dword v2, v112, s[0:1]
	global_load_dword v203, v112, s[0:1] offset:-1024
	global_load_dword v4, v112, s[76:77]
	global_load_dword v205, v112, s[76:77] offset:-1024
	global_load_dword v3, v112, s[34:35]
	global_load_dword v204, v112, s[34:35] offset:-1024
	v_add_u32_e32 v194, s24, v184
	v_lshlrev_b32_e32 v114, 2, v194
	global_load_dword v108, v114, s[40:41]
	global_load_dword v206, v114, s[40:41] offset:-32
	s_branch .Lis1b

.LBB0_449:
	s_andn2_saveexec_b64 s[24:25], s[74:75]
	v_subrev_u32_e32 v26, 0x17900, v151
	v_lshrrev_b32_e32 v26, 2, v26
	v_add3_u32 v26, v151, v145, v26
	ds_write_b128 v26, v[22:25]
